# v16: tile classification flags with fewer VALU/SALU round trips (selected + MoBA loops)
# speedup vs baseline: 1.0128x; 1.0023x over previous
.LBB0_634:
	s_lshl_b32 s0, 1, s0
	s_waitcnt vmcnt(0)
	v_and_b32_e32 v0, s0, v187
	v_and_b32_e32 v66, s0, v188
	v_cmp_ne_u32_e64 s[6:7], 0, v0
	v_cmp_ne_u32_e32 vcc, 0, v66
	v_cmp_le_u32_e64 s[8:9], s85, v143
	v_cmp_le_u32_e64 s[2:3], s85, v177
	s_and_b64 s[8:9], s[8:9], s[6:7]
	s_and_b64 s[2:3], s[2:3], vcc
	s_cmp_lg_u64 s[8:9], 0
	s_cselect_b64 s[8:9], -1, 0
	s_cmp_lg_u64 s[2:3], 0
	s_cselect_b64 s[2:3], -1, 0
	v_cndmask_b32_e64 v0, 0, 1, s[8:9]
	v_cndmask_b32_e64 v167, 0, 1, s[2:3]
	s_or_b64 s[0:1], s[8:9], s[2:3]
	s_and_saveexec_b64 s[54:55], s[0:1]
	s_cbranch_execz .LBB0_646
	s_cmp_eq_u32 s87, 0
	s_cselect_b64 s[58:59], -1, 0
	s_and_b64 s[0:1], s[58:59], exec
	s_cselect_b32 s0, 0, 0x2400
	v_add_u32_e32 v168, s0, v178
	ds_read_b128 v[158:161], v168
	ds_read_b128 v[162:165], v176 offset:53248
	v_cmp_gt_i32_e64 s[4:5], s85, v190
	s_waitcnt lgkmcnt(2)
	v_cndmask_b32_e64 v66, v173, v189, s[6:7]
	ds_read_b128 v[196:199], v168 offset:32
	ds_read_b128 v[202:205], v176 offset:54272
	ds_read_b128 v[206:209], v176 offset:57344
	ds_read_b128 v[210:213], v176 offset:58368
	v_cndmask_b32_e64 v166, 0, v171, s[4:5]
	v_cndmask_b32_e64 v66, v66, 0, s[4:5]
	v_cndmask_b32_e32 v67, v173, v189, vcc
	v_cmp_gt_i32_e64 s[4:5], s85, v191
	v_cndmask_b32_e64 v240, v173, v66, s[8:9]
	s_nop 0
	v_cndmask_b32_e64 v67, v67, 0, s[4:5]
	s_nop 1
	v_cndmask_b32_e64 v241, v173, v67, s[2:3]
	s_waitcnt lgkmcnt(4)
	v_mfma_f32_32x32x16_bf16 v[98:113], v[158:161], v[162:165], 0
	s_waitcnt lgkmcnt(1)
	v_mfma_f32_32x32x16_bf16 v[114:129], v[158:161], v[206:209], 0
	ds_read_b128 v[158:161], v168 offset:4608
	ds_read_b128 v[214:217], v168 offset:4640
	s_waitcnt lgkmcnt(1)
	v_mfma_f32_32x32x16_bf16 v[82:97], v[158:161], v[162:165], 0
	v_mfma_f32_32x32x16_bf16 v[66:81], v[158:161], v[206:209], 0
	v_mfma_f32_32x32x16_bf16 v[98:113], v[196:199], v[202:205], v[98:113]
	v_mfma_f32_32x32x16_bf16 v[114:129], v[196:199], v[210:213], v[114:129]
	ds_read_b128 v[158:161], v168 offset:64
	ds_read_b128 v[162:165], v176 offset:55296
	ds_read_b128 v[196:199], v168 offset:96
	ds_read_b128 v[206:209], v176 offset:56320
	s_waitcnt lgkmcnt(4)
	v_mfma_f32_32x32x16_bf16 v[82:97], v[214:217], v[202:205], v[82:97]
	v_mfma_f32_32x32x16_bf16 v[66:81], v[214:217], v[210:213], v[66:81]
	ds_read_b128 v[202:205], v176 offset:59392
	ds_read_b128 v[210:213], v176 offset:60416
	s_waitcnt lgkmcnt(4)
	v_mfma_f32_32x32x16_bf16 v[98:113], v[158:161], v[162:165], v[98:113]
	s_waitcnt lgkmcnt(1)
	v_mfma_f32_32x32x16_bf16 v[114:129], v[158:161], v[202:205], v[114:129]
	ds_read_b128 v[158:161], v168 offset:4672
	ds_read_b128 v[214:217], v168 offset:4704
	s_waitcnt lgkmcnt(1)
	v_mfma_f32_32x32x16_bf16 v[82:97], v[158:161], v[162:165], v[82:97]
	v_mfma_f32_32x32x16_bf16 v[66:81], v[158:161], v[202:205], v[66:81]
	v_cndmask_b32_e64 v158, 0, v172, s[6:7]
	v_or3_b32 v0, v158, v166, v0
	v_cndmask_b32_e64 v158, v158, v0, s[8:9]
	v_and_b32_e32 v0, 0x100, v158
	v_cmp_ne_u32_e64 s[6:7], 0, v0
	v_add_u32_e32 v0, s60, v192
	v_mfma_f32_32x32x16_bf16 v[98:113], v[196:199], v[206:209], v[98:113]
	v_mfma_f32_32x32x16_bf16 v[114:129], v[196:199], v[210:213], v[114:129]
	s_waitcnt lgkmcnt(0)
	v_mfma_f32_32x32x16_bf16 v[82:97], v[214:217], v[206:209], v[82:97]
	v_mfma_f32_32x32x16_bf16 v[66:81], v[214:217], v[210:213], v[66:81]
	s_and_saveexec_b64 s[8:9], s[6:7]
	s_cbranch_execz .LBB0_641
	v_lshl_add_u32 v206, v0, 2, s92
	v_and_b32_e32 v205, 0x10000, v158
	v_cmp_ne_u32_e64 s[6:7], 0, v205
	v_mov_b32_e32 v207, s93
	s_nop 1
	v_cndmask_b32_e64 v206, v207, v206, s[6:7]
	ds_read_b32 v208, v206 offset:236
	ds_read_b32 v209, v206 offset:232
	ds_read_b32 v210, v206 offset:228
	ds_read_b32 v211, v206 offset:224
	ds_read_b32 v212, v206 offset:204
	ds_read_b32 v213, v206 offset:200
	ds_read_b32 v214, v206 offset:196
	ds_read_b32 v215, v206 offset:192
	ds_read_b32 v216, v206 offset:172
	ds_read_b32 v217, v206 offset:168
	ds_read_b32 v218, v206 offset:164
	ds_read_b32 v219, v206 offset:160
	ds_read_b32 v220, v206 offset:140
	ds_read_b32 v221, v206 offset:136
	ds_read_b32 v222, v206 offset:132
	ds_read_b32 v223, v206 offset:128
	ds_read_b32 v224, v206 offset:108
	ds_read_b32 v225, v206 offset:104
	ds_read_b32 v226, v206 offset:100
	ds_read_b32 v227, v206 offset:96
	ds_read_b32 v228, v206 offset:76
	ds_read_b32 v229, v206 offset:72
	ds_read_b32 v230, v206 offset:68
	ds_read_b32 v231, v206 offset:64
	ds_read_b32 v232, v206 offset:44
	ds_read_b32 v233, v206 offset:40
	ds_read_b32 v234, v206 offset:36
	ds_read_b32 v235, v206 offset:32
	ds_read_b32 v236, v206 offset:12
	ds_read_b32 v237, v206 offset:8
	ds_read_b32 v238, v206 offset:4
	ds_read_b32 v239, v206 offset:0
	s_waitcnt lgkmcnt(14)
	v_pk_add_f32 v[98:99], v[98:99], v[208:209]
	v_pk_add_f32 v[100:101], v[100:101], v[210:211]
	v_pk_add_f32 v[102:103], v[102:103], v[212:213]
	v_pk_add_f32 v[104:105], v[104:105], v[214:215]
	v_pk_add_f32 v[106:107], v[106:107], v[216:217]
	v_pk_add_f32 v[108:109], v[108:109], v[218:219]
	v_pk_add_f32 v[110:111], v[110:111], v[220:221]
	v_pk_add_f32 v[112:113], v[112:113], v[222:223]
	s_waitcnt lgkmcnt(0)
	v_pk_add_f32 v[82:83], v[82:83], v[224:225]
	v_pk_add_f32 v[84:85], v[84:85], v[226:227]
	v_pk_add_f32 v[86:87], v[86:87], v[228:229]
	v_pk_add_f32 v[88:89], v[88:89], v[230:231]
	v_pk_add_f32 v[90:91], v[90:91], v[232:233]
	v_pk_add_f32 v[92:93], v[92:93], v[234:235]
	v_pk_add_f32 v[94:95], v[94:95], v[236:237]
	v_pk_add_f32 v[96:97], v[96:97], v[238:239]

.LBB0_1326:
	s_lshr_b32 s0, s0, 2
	s_lshl_b32 s0, 1, s0
	v_and_b32_e32 v64, s0, v205
	v_and_b32_e32 v65, s0, v175
	v_cmp_ne_u32_e64 s[4:5], 0, v64
	v_cmp_ne_u32_e32 vcc, 0, v65
	v_cmp_le_i32_e64 s[6:7], s18, v206
	v_cmp_le_i32_e64 s[2:3], s18, v207
	s_and_b64 s[6:7], s[6:7], s[4:5]
	s_and_b64 s[2:3], s[2:3], vcc
	s_cmp_lg_u64 s[6:7], 0
	s_cselect_b64 s[6:7], -1, 0
	s_cmp_lg_u64 s[2:3], 0
	s_cselect_b64 s[2:3], -1, 0
	v_cndmask_b32_e64 v64, 0, 1, s[6:7]
	v_cndmask_b32_e64 v168, 0, 1, s[2:3]
	s_or_b64 s[0:1], s[6:7], s[2:3]
	s_and_saveexec_b64 s[12:13], s[0:1]
	s_cbranch_execz .LBB0_1338
	v_add_u32_e32 v65, s19, v208
	v_subrev_u32_e32 v66, 63, v65
	v_cmp_gt_i32_e64 s[8:9], s87, v66
	v_cndmask_b32_e64 v215, 0, v202, s[4:5]
	s_cmp_eq_u32 s97, 0
	v_cndmask_b32_e64 v66, 0, v198, s[8:9]
	v_or3_b32 v216, v215, v66, v64
	s_waitcnt lgkmcnt(8)
	v_cndmask_b32_e64 v64, v203, v212, s[4:5]
	v_cndmask_b32_e64 v64, v64, 0, s[8:9]
	s_cselect_b64 s[8:9], -1, 0
	s_and_b64 s[0:1], s[8:9], exec
	s_cselect_b32 s0, 0, 0x2400
	v_subrev_u32_e32 v65, 31, v65
	v_add_u32_e32 v217, s0, v209
	v_cmp_gt_i32_e64 s[4:5], s87, v65
	v_cndmask_b32_e32 v65, v203, v212, vcc
	ds_read_b128 v[186:189], v217 offset:4608
	ds_read_b128 v[190:193], v217
	ds_read_b128 v[194:197], v217 offset:32
	v_cndmask_b32_e64 v65, v65, 0, s[4:5]
	v_cndmask_b32_e64 v252, v203, v64, s[6:7]
	v_cndmask_b32_e64 v253, v203, v65, s[2:3]
	s_waitcnt lgkmcnt(1)
	v_mfma_f32_32x32x16_bf16 v[96:111], v[190:193], v[128:131], 0
	v_mfma_f32_32x32x16_bf16 v[112:127], v[190:193], v[148:151], 0
	v_mfma_f32_32x32x16_bf16 v[80:95], v[186:189], v[128:131], 0
	v_mfma_f32_32x32x16_bf16 v[64:79], v[186:189], v[148:151], 0
	ds_read_b128 v[186:189], v217 offset:4640
	s_waitcnt lgkmcnt(1)
	v_mfma_f32_32x32x16_bf16 v[96:111], v[194:197], v[132:135], v[96:111]
	v_mfma_f32_32x32x16_bf16 v[112:127], v[194:197], v[140:143], v[112:127]
	s_waitcnt lgkmcnt(0)
	v_mfma_f32_32x32x16_bf16 v[80:95], v[186:189], v[132:135], v[80:95]
	v_mfma_f32_32x32x16_bf16 v[64:79], v[186:189], v[140:143], v[64:79]
	ds_read_b128 v[186:189], v217 offset:64
	ds_read_b128 v[190:193], v217 offset:4672
	s_waitcnt lgkmcnt(1)
	v_mfma_f32_32x32x16_bf16 v[96:111], v[186:189], v[136:139], v[96:111]
	v_mfma_f32_32x32x16_bf16 v[112:127], v[186:189], v[144:147], v[112:127]
	s_waitcnt lgkmcnt(0)
	v_mfma_f32_32x32x16_bf16 v[80:95], v[190:193], v[136:139], v[80:95]
	v_mfma_f32_32x32x16_bf16 v[64:79], v[190:193], v[144:147], v[64:79]
	ds_read_b128 v[186:189], v217 offset:96
	ds_read_b128 v[190:193], v217 offset:4704
	s_waitcnt lgkmcnt(1)
	v_mfma_f32_32x32x16_bf16 v[96:111], v[186:189], v[152:155], v[96:111]
	v_mfma_f32_32x32x16_bf16 v[112:127], v[186:189], v[156:159], v[112:127]
	v_cndmask_b32_e64 v186, v215, v216, s[6:7]
	v_and_b32_e32 v187, 0x100, v186
	v_cmp_ne_u32_e64 s[6:7], 0, v187
	s_waitcnt lgkmcnt(0)
	v_mfma_f32_32x32x16_bf16 v[80:95], v[190:193], v[152:155], v[80:95]
	v_mfma_f32_32x32x16_bf16 v[64:79], v[190:193], v[156:159], v[64:79]
	v_add_u32_e32 v190, s19, v211
	s_and_saveexec_b64 s[14:15], s[6:7]
	s_cbranch_execz .LBB0_1333
	v_lshl_add_u32 v224, v190, 2, s91
	v_and_b32_e32 v186, 0x10000, v186
	v_cmp_ne_u32_e64 s[6:7], 0, v186
	v_mov_b32_e32 v225, 0x1d000
	s_nop 1
	v_cndmask_b32_e64 v224, v225, v224, s[6:7]
	ds_read_b32 v226, v224 offset:236
	ds_read_b32 v227, v224 offset:232
	ds_read_b32 v228, v224 offset:228
	ds_read_b32 v229, v224 offset:224
	ds_read_b32 v230, v224 offset:204
	ds_read_b32 v231, v224 offset:200
	ds_read_b32 v232, v224 offset:196
	ds_read_b32 v233, v224 offset:192
	ds_read_b32 v234, v224 offset:172
	ds_read_b32 v235, v224 offset:168
	ds_read_b32 v236, v224 offset:164
	ds_read_b32 v237, v224 offset:160
	ds_read_b32 v238, v224 offset:140
	ds_read_b32 v239, v224 offset:136
	ds_read_b32 v240, v224 offset:132
	ds_read_b32 v241, v224 offset:128
	ds_read_b32 v242, v224 offset:108
	ds_read_b32 v243, v224 offset:104
	ds_read_b32 v244, v224 offset:100
	ds_read_b32 v245, v224 offset:96
	ds_read_b32 v246, v224 offset:76
	ds_read_b32 v247, v224 offset:72
	ds_read_b32 v248, v224 offset:68
	ds_read_b32 v249, v224 offset:64
	ds_read_b32 v250, v224 offset:44
	ds_read_b32 v251, v224 offset:40
	s_waitcnt lgkmcnt(10)
	v_pk_add_f32 v[96:97], v[96:97], v[226:227]
	v_pk_add_f32 v[98:99], v[98:99], v[228:229]
	v_pk_add_f32 v[100:101], v[100:101], v[230:231]
	v_pk_add_f32 v[102:103], v[102:103], v[232:233]
	v_pk_add_f32 v[104:105], v[104:105], v[234:235]
	v_pk_add_f32 v[106:107], v[106:107], v[236:237]
	v_pk_add_f32 v[108:109], v[108:109], v[238:239]
	v_pk_add_f32 v[110:111], v[110:111], v[240:241]
	ds_read_b32 v226, v224 offset:36
	ds_read_b32 v227, v224 offset:32
	ds_read_b32 v228, v224 offset:12
	ds_read_b32 v229, v224 offset:8
	ds_read_b32 v230, v224 offset:4
	ds_read_b32 v231, v224 offset:0
	s_waitcnt lgkmcnt(6)
	v_pk_add_f32 v[80:81], v[80:81], v[242:243]
	v_pk_add_f32 v[82:83], v[82:83], v[244:245]
	v_pk_add_f32 v[84:85], v[84:85], v[246:247]
	v_pk_add_f32 v[86:87], v[86:87], v[248:249]
	v_pk_add_f32 v[88:89], v[88:89], v[250:251]
	s_waitcnt lgkmcnt(0)
	v_pk_add_f32 v[90:91], v[90:91], v[226:227]
	v_pk_add_f32 v[92:93], v[92:93], v[228:229]
	v_pk_add_f32 v[94:95], v[94:95], v[230:231]
